# setup phase weight conversion loop rotated: next super-tile's 8 global loads issued before the current tile's LDS-read/convert/store tail
# baseline (speedup 1.0000x reference)
; __device__ __forceinline__ unsigned cvt_pk_bf16(float lo, float hi) { unsigned r; asm volatile("v_cvt_pk_bf16_f32 %0, %1, %2" : "=v"(r) : "v"(lo), "v"(hi)); return r; }
; __device__ __forceinline__ void p0_setup(const KQ p_in, float* sm, unsigned* mod_word) {
;     ...
;             const int ntn = N / 64; const int k0 = (tl / ntn) * 64, n0 = (tl % ntn) * 64;
;             f32x4 ld[8];
; #pragma unroll
;             for (int i = 0; i < 8; ++i) ld[i] = *(const f32x4*)(src + (size_t)(k0 + i * 8 + (tid >> 6)) * N + n0 + (tid & 63) * 4);
;             __syncthreads();
; #pragma unroll
;             for (int i = 0; i < 8; ++i) *(f32x4*)(tile + (i * 8 + (tid >> 6)) * 260 + (tid & 63) * 4) = ld[i];
;             __syncthreads();
;             {
;                 const int n = tid >> 1, kh = (tid & 1) * 32; const int gn = n0 + n;
;                 float sc_ = 1.0f; int row = gn;
;                 if (mode == 1) row = 256 * (gn >> 7) + (gn & 127);
;                 else if (mode == 2) row = 256 * (gn >> 7) + 128 + (gn & 127);
;                 else if (mode == 3) { if (gn < 512) sc_ = 0.125f * 1.44269504f; else if (gn >= 1792 && gn < 2304) sc_ = 0.125f; }
; #pragma unroll
;                 for (int q = 0; q < 4; ++q) {
;                     float v[8];
; #pragma unroll
;                     for (int jj = 0; jj < 8; ++jj) v[jj] = tile[(kh + q * 8 + jj) * 260 + n] * sc_;
;                     u32x4 o4; o4.x = pg8::cvt_pk_bf16(v[0], v[1]); o4.y = pg8::cvt_pk_bf16(v[2], v[3]); o4.z = pg8::cvt_pk_bf16(v[4], v[5]); o4.w = pg8::cvt_pk_bf16(v[6], v[7]);
;                     *(u32x4*)(dst + (size_t)row * K + k0 + kh + q * 8) = o4;
;                 }
.LBB0_52:
	s_or_b64 exec, exec, s[14:15]
	s_cmpk_gt_i32 s96, 0x145f
	s_cbranch_scc1 .LBB0_101
	s_add_u32 s2, s12, 0x9f00000
	s_addc_u32 s3, s13, 0
	s_add_u32 s22, s12, 0x9300000
	s_addc_u32 s23, s13, 0
	s_add_u32 s24, s12, 0x8f00000
	s_addc_u32 s25, s13, 0
	s_add_u32 s26, s12, 0x8400000
	v_lshlrev_b32_e32 v2, 5, v52
	s_addc_u32 s27, s13, 0
	v_ashrrev_i32_e32 v4, 1, v52
	v_and_b32_e32 v6, 32, v2
	s_movk_i32 s0, 0x410
	s_add_u32 s28, s12, 0x5800000
	v_lshlrev_b32_e32 v0, 2, v80
	v_mov_b32_e32 v1, 0
	v_lshl_add_u32 v5, v80, 4, 0
	v_lshl_add_u32 v7, v4, 2, 0
	v_mul_u32_u24_e32 v8, 0x410, v6
	v_mul_lo_u32 v9, v81, s0
	s_addc_u32 s29, s13, 0
	s_mov_b32 s1, 0
	s_lshl_b32 s30, s96, 2
	s_lshl_b32 s31, s44, 2
	s_add_i32 s34, 0, 0x23ee0
	s_add_i32 s35, 0, 0x23e78
	s_add_i32 s36, 0, 0x23e70
	s_add_i32 s37, 0, 0x23e58
	s_add_i32 s38, 0, 0x23e50
	s_add_i32 s39, 0, 0x23e48
	s_add_i32 s46, 0, 0x23e40
	v_lshlrev_b32_e32 v2, 2, v0
	v_mov_b32_e32 v3, v1
	v_add_u32_e32 v5, v5, v9
	s_movk_i32 s47, 0x200
	s_movk_i32 s48, 0x1ff
	s_movk_i32 s49, 0xff00
	s_movk_i32 s50, 0x80
	v_lshlrev_b32_e32 v0, 1, v6
	v_add_u32_e32 v6, v7, v8
	v_mov_b32_e32 v7, 0x3e000000
	v_mov_b32_e32 v8, 0x3e38aa3b
	s_mov_b32 s51, s96
	s_mov_b32 s101, 0
	s_branch .LBB0_55
.LBB0_54:
	v_ashrrev_i32_e32 v10, 31, v11
	v_mul_lo_u32 v12, s11, v11
	v_mul_lo_u32 v13, s10, v10
	v_mad_u64_u32 v[10:11], s[4:5], s10, v11, 0
	v_add3_u32 v11, v11, v13, v12
	v_lshl_add_u64 v[10:11], v[10:11], 1, s[6:7]
	s_ashr_i32 s19, s18, 31
	v_lshl_add_u64 v[10:11], s[18:19], 1, v[10:11]
	v_lshl_add_u64 v[14:15], v[10:11], 0, v[0:1]
	v_mov_b32_e32 v208, v14
	v_mov_b32_e32 v209, v15
	v_mov_b32_e32 v210, v9
	s_add_i32 s51, s51, s44
	s_add_i32 s30, s30, s31
	s_mov_b32 s101, 1
	s_cmpk_gt_i32 s51, 0x145f
	s_cbranch_scc0 .LBB0_55
	ds_read_b32 v212, v6
	ds_read_b32 v213, v6 offset:1040
	ds_read_b32 v214, v6 offset:2080
	ds_read_b32 v215, v6 offset:3120
	ds_read_b32 v216, v6 offset:4160
	ds_read_b32 v217, v6 offset:5200
	ds_read_b32 v218, v6 offset:6240
	ds_read_b32 v219, v6 offset:7280
	s_waitcnt lgkmcnt(7)
	v_mul_f32_e32 v212, v210, v212
	s_waitcnt lgkmcnt(6)
	v_mul_f32_e32 v213, v210, v213
	s_waitcnt lgkmcnt(5)
	v_mul_f32_e32 v214, v210, v214
	s_waitcnt lgkmcnt(4)
	v_mul_f32_e32 v215, v210, v215
	s_waitcnt lgkmcnt(3)
	v_mul_f32_e32 v216, v210, v216
	s_waitcnt lgkmcnt(2)
	v_mul_f32_e32 v217, v210, v217
	s_waitcnt lgkmcnt(1)
	v_mul_f32_e32 v218, v210, v218
	s_waitcnt lgkmcnt(0)
	v_mul_f32_e32 v219, v210, v219
	v_cvt_pk_bf16_f32 v212, v212, v213
	v_cvt_pk_bf16_f32 v213, v214, v215
	v_cvt_pk_bf16_f32 v214, v216, v217
	v_cvt_pk_bf16_f32 v215, v218, v219
	global_store_dwordx4 v[208:209], v[212:215], off
	ds_read_b32 v212, v6 offset:8320
	ds_read_b32 v213, v6 offset:9360
	ds_read_b32 v214, v6 offset:10400
	ds_read_b32 v215, v6 offset:11440
	ds_read_b32 v216, v6 offset:12480
	ds_read_b32 v217, v6 offset:13520
	ds_read_b32 v218, v6 offset:14560
	ds_read_b32 v219, v6 offset:15600
	s_waitcnt lgkmcnt(0)
	v_mul_f32_e32 v212, v210, v212
	v_mul_f32_e32 v213, v210, v213
	v_mul_f32_e32 v214, v210, v214
	v_mul_f32_e32 v215, v210, v215
	v_mul_f32_e32 v216, v210, v216
	v_mul_f32_e32 v217, v210, v217
	v_mul_f32_e32 v218, v210, v218
	v_mul_f32_e32 v219, v210, v219
	v_cvt_pk_bf16_f32 v212, v212, v213
	v_cvt_pk_bf16_f32 v213, v214, v215
	v_cvt_pk_bf16_f32 v214, v216, v217
	v_cvt_pk_bf16_f32 v215, v218, v219
	global_store_dwordx4 v[208:209], v[212:215], off offset:16
	ds_read_b32 v212, v6 offset:16640
	ds_read_b32 v213, v6 offset:17680
	ds_read_b32 v214, v6 offset:18720
	ds_read_b32 v215, v6 offset:19760
	ds_read_b32 v216, v6 offset:20800
	ds_read_b32 v217, v6 offset:21840
	ds_read_b32 v218, v6 offset:22880
	ds_read_b32 v219, v6 offset:23920
	s_waitcnt lgkmcnt(0)
	v_mul_f32_e32 v212, v210, v212
	v_mul_f32_e32 v213, v210, v213
	v_mul_f32_e32 v214, v210, v214
	v_mul_f32_e32 v215, v210, v215
	v_mul_f32_e32 v216, v210, v216
	v_mul_f32_e32 v217, v210, v217
	v_mul_f32_e32 v218, v210, v218
	v_mul_f32_e32 v219, v210, v219
	v_cvt_pk_bf16_f32 v212, v212, v213
	v_cvt_pk_bf16_f32 v213, v214, v215
	v_cvt_pk_bf16_f32 v214, v216, v217
	v_cvt_pk_bf16_f32 v215, v218, v219
	global_store_dwordx4 v[208:209], v[212:215], off offset:32
	ds_read_b32 v212, v6 offset:24960
	ds_read_b32 v213, v6 offset:26000
	ds_read_b32 v214, v6 offset:27040
	ds_read_b32 v215, v6 offset:28080
	ds_read_b32 v216, v6 offset:29120
	ds_read_b32 v217, v6 offset:30160
	ds_read_b32 v218, v6 offset:31200
	ds_read_b32 v219, v6 offset:32240
	s_waitcnt lgkmcnt(0)
	v_mul_f32_e32 v212, v210, v212
	v_mul_f32_e32 v213, v210, v213
	v_mul_f32_e32 v214, v210, v214
	v_mul_f32_e32 v215, v210, v215
	v_mul_f32_e32 v216, v210, v216
	v_mul_f32_e32 v217, v210, v217
	v_mul_f32_e32 v218, v210, v218
	v_mul_f32_e32 v210, v210, v219
	v_cvt_pk_bf16_f32 v212, v212, v213
	v_cvt_pk_bf16_f32 v213, v214, v215
	v_cvt_pk_bf16_f32 v214, v216, v217
	v_cvt_pk_bf16_f32 v215, v218, v210
	global_store_dwordx4 v[208:209], v[212:215], off offset:48
	s_branch .LBB0_101

; __device__ __forceinline__ unsigned cvt_pk_bf16(float lo, float hi) { unsigned r; asm volatile("v_cvt_pk_bf16_f32 %0, %1, %2" : "=v"(r) : "v"(lo), "v"(hi)); return r; }
; __device__ __forceinline__ void p0_setup(const KQ p_in, float* sm, unsigned* mod_word) {
;     ...
;             const int ntn = N / 64; const int k0 = (tl / ntn) * 64, n0 = (tl % ntn) * 64;
;             f32x4 ld[8];
; #pragma unroll
;             for (int i = 0; i < 8; ++i) ld[i] = *(const f32x4*)(src + (size_t)(k0 + i * 8 + (tid >> 6)) * N + n0 + (tid & 63) * 4);
;             __syncthreads();
; #pragma unroll
;             for (int i = 0; i < 8; ++i) *(f32x4*)(tile + (i * 8 + (tid >> 6)) * 260 + (tid & 63) * 4) = ld[i];
;             __syncthreads();
;             {
;                 const int n = tid >> 1, kh = (tid & 1) * 32; const int gn = n0 + n;
;                 float sc_ = 1.0f; int row = gn;
;                 if (mode == 1) row = 256 * (gn >> 7) + (gn & 127);
;                 else if (mode == 2) row = 256 * (gn >> 7) + 128 + (gn & 127);
;                 else if (mode == 3) { if (gn < 512) sc_ = 0.125f * 1.44269504f; else if (gn >= 1792 && gn < 2304) sc_ = 0.125f; }
; #pragma unroll
;                 for (int q = 0; q < 4; ++q) {
;                     float v[8];
; #pragma unroll
;                     for (int jj = 0; jj < 8; ++jj) v[jj] = tile[(kh + q * 8 + jj) * 260 + n] * sc_;
;                     u32x4 o4; o4.x = pg8::cvt_pk_bf16(v[0], v[1]); o4.y = pg8::cvt_pk_bf16(v[2], v[3]); o4.z = pg8::cvt_pk_bf16(v[4], v[5]); o4.w = pg8::cvt_pk_bf16(v[6], v[7]);
;                     *(u32x4*)(dst + (size_t)row * K + k0 + kh + q * 8) = o4;
.LBB0_93:
	s_lshr_b32 s21, s0, 6
	v_cvt_f32_i32_e32 v9, s21
	s_sext_i32_i16 s18, s20
	v_cvt_f32_i32_e32 v10, s18
	s_ashr_i32 s18, s18, 30
	v_rcp_iflag_f32_e32 v11, v9
	s_or_b32 s52, s18, 1
	v_mul_f32_e32 v11, v10, v11
	v_trunc_f32_e32 v11, v11
	v_fma_f32 v10, -v11, v9, v10
	v_cvt_i32_f32_e32 v11, v11
	v_cmp_ge_f32_e64 s[18:19], |v10|, v9
	s_and_b64 s[18:19], s[18:19], exec
	s_cselect_b32 s18, s52, 0
	v_readfirstlane_b32 s19, v11
	s_add_i32 s18, s19, s18
	s_sext_i32_i16 s19, s18
	s_mul_i32 s21, s18, s21
	s_lshl_b32 s18, s19, 6
	s_sub_i32 s19, s20, s21
	s_sext_i32_i16 s19, s19
	s_lshl_b32 s20, s19, 6
	s_ashr_i32 s21, s20, 31
	s_lshl_b64 s[52:53], s[20:21], 2
	v_add_u32_e32 v9, s18, v81
	s_add_u32 s8, s8, s52
	s_addc_u32 s9, s9, s53
	v_add_u32_e32 v18, 16, v9
	v_add_u32_e32 v26, 32, v9
	v_lshl_add_u64 v[34:35], s[8:9], 0, v[2:3]
	v_mad_u64_u32 v[10:11], s[8:9], v9, s0, 0
	v_ashrrev_i32_e32 v21, 31, v18
	v_mad_u64_u32 v[18:19], s[8:9], v18, s0, 0
	v_ashrrev_i32_e32 v29, 31, v26
	v_mad_u64_u32 v[26:27], s[8:9], v26, s0, 0
	v_add_u32_e32 v36, 48, v9
	v_ashrrev_i32_e32 v13, 31, v9
	v_mov_b32_e32 v12, v11
	v_mov_b32_e32 v20, v19
	v_mov_b32_e32 v28, v27
	v_ashrrev_i32_e32 v39, 31, v36
	v_mad_u64_u32 v[36:37], s[8:9], v36, s0, 0
	v_mad_u64_u32 v[12:13], s[8:9], v13, s0, v[12:13]
	v_mad_u64_u32 v[20:21], s[8:9], v21, s0, v[20:21]
	v_mad_u64_u32 v[28:29], s[8:9], v29, s0, v[28:29]
	v_mov_b32_e32 v38, v37
	v_mov_b32_e32 v11, v12
	v_add_u32_e32 v12, 8, v9
	v_mov_b32_e32 v19, v20
	v_add_u32_e32 v20, 24, v9
	v_mov_b32_e32 v27, v28
	v_add_u32_e32 v28, 40, v9
	v_mad_u64_u32 v[38:39], s[8:9], v39, s0, v[38:39]
	v_add_u32_e32 v9, 56, v9
	v_ashrrev_i32_e32 v15, 31, v12
	v_mad_u64_u32 v[12:13], s[8:9], v12, s0, 0
	v_ashrrev_i32_e32 v23, 31, v20
	v_mad_u64_u32 v[20:21], s[8:9], v20, s0, 0
	v_ashrrev_i32_e32 v31, 31, v28
	v_mad_u64_u32 v[28:29], s[8:9], v28, s0, 0
	v_mov_b32_e32 v37, v38
	v_mad_u64_u32 v[38:39], s[8:9], v9, s0, 0
	v_mov_b32_e32 v14, v13
	v_mov_b32_e32 v22, v21
	v_mov_b32_e32 v30, v29
	v_ashrrev_i32_e32 v41, 31, v9
	v_mov_b32_e32 v40, v39
	v_mad_u64_u32 v[14:15], s[8:9], v15, s0, v[14:15]
	v_mad_u64_u32 v[22:23], s[8:9], v23, s0, v[22:23]
	v_mad_u64_u32 v[30:31], s[8:9], v31, s0, v[30:31]
	v_mad_u64_u32 v[40:41], s[8:9], v41, s0, v[40:41]
	v_mov_b32_e32 v13, v14
	v_mov_b32_e32 v21, v22
	v_mov_b32_e32 v29, v30
	v_mov_b32_e32 v39, v40
	v_lshl_add_u64 v[10:11], v[10:11], 2, v[34:35]
	v_lshl_add_u64 v[14:15], v[12:13], 2, v[34:35]
	v_lshl_add_u64 v[18:19], v[18:19], 2, v[34:35]
	v_lshl_add_u64 v[22:23], v[20:21], 2, v[34:35]
	v_lshl_add_u64 v[26:27], v[26:27], 2, v[34:35]
	v_lshl_add_u64 v[30:31], v[28:29], 2, v[34:35]
	v_lshl_add_u64 v[36:37], v[36:37], 2, v[34:35]
	v_lshl_add_u64 v[38:39], v[38:39], 2, v[34:35]
	global_load_dwordx4 v[10:13], v[10:11], off
	s_nop 0
	global_load_dwordx4 v[14:17], v[14:15], off
	s_nop 0
	global_load_dwordx4 v[18:21], v[18:19], off
	s_nop 0
	global_load_dwordx4 v[22:25], v[22:23], off
	s_nop 0
	global_load_dwordx4 v[26:29], v[26:27], off
	s_nop 0
	global_load_dwordx4 v[30:33], v[30:31], off
	s_nop 0
	global_load_dwordx4 v[34:37], v[36:37], off
	s_nop 0
	global_load_dwordx4 v[38:41], v[38:39], off
	s_cmp_eq_u32 s101, 0
	s_cbranch_scc1 .Lwc_notail
	ds_read_b32 v212, v6
	ds_read_b32 v213, v6 offset:1040
	ds_read_b32 v214, v6 offset:2080
	ds_read_b32 v215, v6 offset:3120
	ds_read_b32 v216, v6 offset:4160
	ds_read_b32 v217, v6 offset:5200
	ds_read_b32 v218, v6 offset:6240
	ds_read_b32 v219, v6 offset:7280
	s_waitcnt lgkmcnt(7)
	v_mul_f32_e32 v212, v210, v212
	s_waitcnt lgkmcnt(6)
	v_mul_f32_e32 v213, v210, v213
	s_waitcnt lgkmcnt(5)
	v_mul_f32_e32 v214, v210, v214
	s_waitcnt lgkmcnt(4)
	v_mul_f32_e32 v215, v210, v215
	s_waitcnt lgkmcnt(3)
	v_mul_f32_e32 v216, v210, v216
	s_waitcnt lgkmcnt(2)
	v_mul_f32_e32 v217, v210, v217
	s_waitcnt lgkmcnt(1)
	v_mul_f32_e32 v218, v210, v218
	s_waitcnt lgkmcnt(0)
	v_mul_f32_e32 v219, v210, v219
	v_cvt_pk_bf16_f32 v212, v212, v213
	v_cvt_pk_bf16_f32 v213, v214, v215
	v_cvt_pk_bf16_f32 v214, v216, v217
	v_cvt_pk_bf16_f32 v215, v218, v219
	global_store_dwordx4 v[208:209], v[212:215], off
	ds_read_b32 v212, v6 offset:8320
	ds_read_b32 v213, v6 offset:9360
	ds_read_b32 v214, v6 offset:10400
	ds_read_b32 v215, v6 offset:11440
	ds_read_b32 v216, v6 offset:12480
	ds_read_b32 v217, v6 offset:13520
	ds_read_b32 v218, v6 offset:14560
	ds_read_b32 v219, v6 offset:15600
	s_waitcnt lgkmcnt(0)
	v_mul_f32_e32 v212, v210, v212
	v_mul_f32_e32 v213, v210, v213
	v_mul_f32_e32 v214, v210, v214
	v_mul_f32_e32 v215, v210, v215
	v_mul_f32_e32 v216, v210, v216
	v_mul_f32_e32 v217, v210, v217
	v_mul_f32_e32 v218, v210, v218
	v_mul_f32_e32 v219, v210, v219
	v_cvt_pk_bf16_f32 v212, v212, v213
	v_cvt_pk_bf16_f32 v213, v214, v215
	v_cvt_pk_bf16_f32 v214, v216, v217
	v_cvt_pk_bf16_f32 v215, v218, v219
	global_store_dwordx4 v[208:209], v[212:215], off offset:16
	ds_read_b32 v212, v6 offset:16640
	ds_read_b32 v213, v6 offset:17680
	ds_read_b32 v214, v6 offset:18720
	ds_read_b32 v215, v6 offset:19760
	ds_read_b32 v216, v6 offset:20800
	ds_read_b32 v217, v6 offset:21840
	ds_read_b32 v218, v6 offset:22880
	ds_read_b32 v219, v6 offset:23920
	s_waitcnt lgkmcnt(0)
	v_mul_f32_e32 v212, v210, v212
	v_mul_f32_e32 v213, v210, v213
	v_mul_f32_e32 v214, v210, v214
	v_mul_f32_e32 v215, v210, v215
	v_mul_f32_e32 v216, v210, v216
	v_mul_f32_e32 v217, v210, v217
	v_mul_f32_e32 v218, v210, v218
	v_mul_f32_e32 v219, v210, v219
	v_cvt_pk_bf16_f32 v212, v212, v213
	v_cvt_pk_bf16_f32 v213, v214, v215
	v_cvt_pk_bf16_f32 v214, v216, v217
	v_cvt_pk_bf16_f32 v215, v218, v219
	global_store_dwordx4 v[208:209], v[212:215], off offset:32
	ds_read_b32 v212, v6 offset:24960
	ds_read_b32 v213, v6 offset:26000
	ds_read_b32 v214, v6 offset:27040
	ds_read_b32 v215, v6 offset:28080
	ds_read_b32 v216, v6 offset:29120
	ds_read_b32 v217, v6 offset:30160
	ds_read_b32 v218, v6 offset:31200
	ds_read_b32 v219, v6 offset:32240
	s_waitcnt lgkmcnt(0)
	v_mul_f32_e32 v212, v210, v212
	v_mul_f32_e32 v213, v210, v213
	v_mul_f32_e32 v214, v210, v214
	v_mul_f32_e32 v215, v210, v215
	v_mul_f32_e32 v216, v210, v216
	v_mul_f32_e32 v217, v210, v217
	v_mul_f32_e32 v218, v210, v218
	v_mul_f32_e32 v210, v210, v219
	v_cvt_pk_bf16_f32 v212, v212, v213
	v_cvt_pk_bf16_f32 v213, v214, v215
	v_cvt_pk_bf16_f32 v214, v216, v217
	v_cvt_pk_bf16_f32 v215, v218, v210
	global_store_dwordx4 v[208:209], v[212:215], off offset:48
.Lwc_notail:
	s_mov_b64 s[8:9], -1
	s_waitcnt lgkmcnt(0)
	s_barrier
	s_and_b64 vcc, exec, s[4:5]
	s_cmp_eq_u32 s101, 0
	s_cbranch_scc1 .Lwc_first
	s_waitcnt vmcnt(4)
	s_branch .Lwc_go

; __device__ __forceinline__ void p0_setup(const KQ p_in, float* sm, unsigned* mod_word) {
;     ...
;             __syncthreads();
; #pragma unroll
;             for (int i = 0; i < 8; ++i) *(f32x4*)(tile + (i * 8 + (tid >> 6)) * 260 + (tid & 63) * 4) = ld[i];
;             __syncthreads();
;             {
;                 const int n = tid >> 1, kh = (tid & 1) * 32; const int gn = n0 + n;
;                 float sc_ = 1.0f; int row = gn;
;                 if (mode == 1) row = 256 * (gn >> 7) + (gn & 127);
;                 else if (mode == 2) row = 256 * (gn >> 7) + 128 + (gn & 127);
;                 else if (mode == 3) { if (gn < 512) sc_ = 0.125f * 1.44269504f; else if (gn >= 1792 && gn < 2304) sc_ = 0.125f; }
.Lwc_go:
	ds_write_b128 v5, v[10:13]
	ds_write_b128 v5, v[14:17] offset:8320
	ds_write_b128 v5, v[18:21] offset:16640
	ds_write_b128 v5, v[22:25] offset:24960
	ds_write_b128 v5, v[26:29] offset:33280
	ds_write_b128 v5, v[30:33] offset:41600
	ds_write_b128 v5, v[34:37] offset:49920
	ds_write_b128 v5, v[38:41] offset:58240
	v_add_u32_e32 v10, s20, v4
	s_waitcnt lgkmcnt(0)
	s_barrier
	s_cbranch_vccz .LBB0_99
	s_xor_b64 s[8:9], s[16:17], -1
	s_mov_b64 s[4:5], -1
	s_and_b64 vcc, exec, s[8:9]
	s_cbranch_vccz .LBB0_96
	v_add_u32_e32 v9, 0xfffff900, v10
	v_cmp_gt_u32_e32 vcc, s47, v9
	s_mov_b64 s[4:5], 0
	s_nop 0
	v_cndmask_b32_e32 v9, 1.0, v7, vcc
	v_cmp_lt_i32_e32 vcc, s48, v10
	s_nop 1
	v_cndmask_b32_e32 v9, v8, v9, vcc
	v_cndmask_b32_e64 v9, 1.0, v9, s[14:15]
